# S33: S32 + attention epilogue: next row's two X-exchange ds_read2_b32 prefetched one row ahead into fresh registers (counted lgkmcnt, leftover waits removed)
# speedup vs baseline: 1.0067x; 1.0033x over previous
; __device__ __forceinline__ unsigned f2bf(float f) { unsigned u = __builtin_bit_cast(unsigned, f); return (u + 0x7fffu + ((u >> 16) & 1u)) >> 16; }
; __device__ __forceinline__ int crow(int r, int hi) { return (r & 3) + 8 * (r >> 2) + 4 * hi; }
; __device__ __forceinline__ void attn_unit(const bf16* __restrict__ Qb, const bf16* __restrict__ Kh, const bf16* __restrict__ Vh, int klat0, int nlt, int kctx0, int NT,
;                                           float lam, float post, const float* __restrict__ subw, bf16* __restrict__ Ob, char* lds) {
;     ...
;     float sw[4];
; #pragma unroll
;     for (int d0 = 0; d0 < 4; ++d0) sw[d0] = subw[d0 * 32 + r32_e] * post;
;     bf16* Ow = Ob + (long)(wq_e * 32) * DM;
; #pragma unroll
;     for (int r = 0; r < 16; ++r) { const int orow = crow(r, hi_e); float v[4]; float ss = 0.f;
; #pragma unroll
;       for (int d0 = 0; d0 < 4; ++d0) { v[d0] = o[d0][r] - lam * X[(wq_e * 32 + orow) * 128 + d0 * 32 + r32_e]; ss += v[d0] * v[d0]; }
;       ss += __shfl_xor(ss, 1); ss += __shfl_xor(ss, 2); ss += __shfl_xor(ss, 4); ss += __shfl_xor(ss, 8); ss += __shfl_xor(ss, 16);
;       const float rs = 1.0f / sqrtf(ss * (1.0f / 128.0f) + LN_EPS);
; #pragma unroll
;       for (int d0 = 0; d0 < 4; ++d0) Ow[(long)orow * DM + d0 * 32 + r32_e] = (bf16)f2bf(v[d0] * rs * sw[d0]); }
.LBB0_795:
	s_andn2_b64 vcc, exec, s[6:7]
	s_waitcnt lgkmcnt(0)
	s_barrier
	s_cbranch_vccnz .LBB0_714
	v_lshlrev_b32_e32 v30, 2, v139
	v_ashrrev_i32_e32 v139, 31, v138
	v_lshl_add_u64 v[4:5], v[138:139], 2, s[2:3]
	global_load_dword v8, v[4:5], off
	s_lshl_b64 s[0:1], s[4:5], 12
	v_readlane_b32 s4, v251, 21
	s_add_u32 s0, s4, s0
	v_readlane_b32 s4, v251, 22
	s_addc_u32 s1, s4, s1
	s_mov_b32 s4, 0xf800000
	s_add_u32 s0, s0, s16
	s_addc_u32 s1, s1, 0
	v_ashrrev_i32_e32 v31, 31, v30
	v_add_u32_e32 v28, 8, v30
	v_add_u32_e32 v26, 9, v30
	v_add_u32_e32 v24, 10, v30
	v_add_u32_e32 v22, 11, v30
	v_add_u32_e32 v20, 16, v30
	v_add_u32_e32 v18, 17, v30
	v_add_u32_e32 v16, 18, v30
	v_add_u32_e32 v14, 19, v30
	v_add_u32_e32 v12, 24, v30
	v_add_u32_e32 v10, 25, v30
	v_add_u32_e32 v6, 26, v30
	v_add_u32_e32 v2, 27, v30
	v_ashrrev_i32_e32 v29, 31, v28
	v_ashrrev_i32_e32 v27, 31, v26
	v_ashrrev_i32_e32 v25, 31, v24
	v_ashrrev_i32_e32 v23, 31, v22
	v_ashrrev_i32_e32 v21, 31, v20
	v_ashrrev_i32_e32 v19, 31, v18
	v_ashrrev_i32_e32 v17, 31, v16
	v_ashrrev_i32_e32 v15, 31, v14
	v_ashrrev_i32_e32 v13, 31, v12
	v_ashrrev_i32_e32 v11, 31, v10
	v_ashrrev_i32_e32 v7, 31, v6
	v_ashrrev_i32_e32 v3, 31, v2
	s_waitcnt vmcnt(0)
	v_mul_f32_e32 v34, v161, v8
	global_load_dword v8, v[4:5], off offset:128
	s_waitcnt vmcnt(0)
	v_mul_f32_e32 v35, v161, v8
	global_load_dword v8, v[4:5], off offset:256
	s_waitcnt vmcnt(0)
	v_mul_f32_e32 v36, v161, v8
	global_load_dword v4, v[4:5], off offset:384
	v_lshlrev_b32_e32 v8, 5, v88
	v_ashrrev_i32_e32 v9, 31, v8
	s_waitcnt vmcnt(0)
	v_mul_f32_e32 v37, v161, v4
	v_lshlrev_b64 v[4:5], 12, v[8:9]
	v_add_u32_e32 v9, v30, v8
	v_lshl_add_u32 v9, v9, 7, v138
	v_lshl_add_u32 v9, v9, 2, 0
	ds_read2_b32 v[98:99], v9 offset1:32
	v_lshl_add_u64 v[4:5], s[0:1], 0, v[4:5]
	v_lshl_add_u64 v[4:5], v[138:139], 1, v[4:5]
	s_waitcnt lgkmcnt(0)
	v_fma_f32 v88, -v160, v98, v108
	v_fma_f32 v97, -v160, v99, v109
	ds_read2_b32 v[98:99], v9 offset0:64 offset1:96
	v_mul_f32_e32 v100, v97, v97
	v_fmac_f32_e32 v100, v88, v88
	s_waitcnt lgkmcnt(0)
	v_or_b32_e32 v245, 1, v30
	v_add_u32_e32 v244, v245, v8
	v_lshl_add_u32 v244, v244, 7, v138
	v_lshl_add_u32 v244, v244, 2, 0
	ds_read2_b32 v[240:241], v244 offset1:32
	ds_read2_b32 v[242:243], v244 offset0:64 offset1:96
	v_fma_f32 v9, -v160, v98, v106
	v_fmac_f32_e32 v100, v9, v9
	v_fma_f32 v101, -v160, v99, v107
	v_fmac_f32_e32 v100, v101, v101
	s_nop 1
	v_mov_b32_dpp v98, v100 quad_perm:[1,0,3,2] row_mask:0xf bank_mask:0xf
	v_add_f32_e32 v98, v100, v98
	s_nop 1
	v_mov_b32_dpp v99, v98 quad_perm:[2,3,0,1] row_mask:0xf bank_mask:0xf
	v_add_f32_e32 v98, v98, v99
	s_nop 1
	v_mov_b32_dpp v99, v98 row_half_mirror row_mask:0xf bank_mask:0xf
	v_add_f32_e32 v98, v98, v99
	s_nop 1
	v_mov_b32_dpp v99, v98 row_mirror row_mask:0xf bank_mask:0xf
	v_add_f32_e32 v98, v98, v99
	v_mov_b32_e32 v99, v98
	s_nop 1
	v_permlane16_swap_b32_e32 v98, v99
	v_add_f32_e32 v98, v98, v99
	v_fmamk_f32 v98, v98, 0x3c000000, v179
	v_cmp_gt_f32_e32 vcc, s4, v98
	v_mul_f32_e32 v99, 0x4f800000, v98
	s_nop 0
	v_cndmask_b32_e32 v98, v98, v99, vcc
	v_sqrt_f32_e32 v99, v98
	s_nop 0
	v_add_u32_e32 v100, -1, v99
	v_fma_f32 v102, -v100, v99, v98
	v_cmp_ge_f32_e64 s[0:1], 0, v102
	v_add_u32_e32 v102, 1, v99
	s_nop 0
	v_cndmask_b32_e64 v100, v99, v100, s[0:1]
	v_fma_f32 v99, -v102, v99, v98
	v_cmp_lt_f32_e64 s[0:1], 0, v99
	s_nop 1
	v_cndmask_b32_e64 v99, v100, v102, s[0:1]
	v_mul_f32_e32 v100, 0x37800000, v99
	v_cndmask_b32_e32 v99, v99, v100, vcc
	v_cmp_class_f32_e32 vcc, v98, v180
	s_nop 1
	v_cndmask_b32_e32 v98, v99, v98, vcc
	v_div_scale_f32 v99, s[0:1], v98, v98, 1.0
	v_rcp_f32_e32 v100, v99
	s_nop 0
	v_fma_f32 v102, -v99, v100, 1.0
	v_fmac_f32_e32 v100, v102, v100
	v_div_scale_f32 v102, vcc, 1.0, v98, 1.0
	v_mul_f32_e32 v103, v102, v100
	v_fma_f32 v104, -v99, v103, v102
	v_fmac_f32_e32 v103, v104, v100
	v_fma_f32 v99, -v99, v103, v102
	v_div_fmas_f32 v99, v99, v100, v103
	v_div_fixup_f32 v100, v99, v98, 1.0
	v_lshlrev_b64 v[98:99], 12, v[30:31]
	v_mul_f32_e32 v31, v88, v100
	v_mul_f32_e32 v31, v34, v31
	v_bfe_u32 v88, v31, 16, 1
	v_lshl_add_u64 v[98:99], v[4:5], 0, v[98:99]
	v_add3_u32 v31, v31, v88, s70
	global_store_short_d16_hi v[98:99], v31, off
	v_mul_f32_e32 v31, v97, v100
	v_mul_f32_e32 v31, v35, v31
	v_bfe_u32 v88, v31, 16, 1
	v_mul_f32_e32 v9, v9, v100
	v_add3_u32 v31, v31, v88, s70
	v_mul_f32_e32 v9, v36, v9
	global_store_short_d16_hi v[98:99], v31, off offset:64
	v_bfe_u32 v31, v9, 16, 1
	v_add3_u32 v9, v9, v31, s70
	global_store_short_d16_hi v[98:99], v9, off offset:128
	v_mul_f32_e32 v9, v101, v100
	v_mul_f32_e32 v9, v37, v9
	v_bfe_u32 v31, v9, 16, 1
	v_add3_u32 v9, v9, v31, s70
	global_store_short_d16_hi v[98:99], v9, off offset:192
	v_or_b32_e32 v98, 1, v30
	v_add_u32_e32 v9, v98, v8
	v_lshl_add_u32 v9, v9, 7, v138
	v_lshl_add_u32 v9, v9, 2, 0
	s_waitcnt lgkmcnt(1)
	v_fma_f32 v88, -v160, v241, v96
	v_fma_f32 v31, -v160, v240, v95
	v_mul_f32_e32 v95, v88, v88
	v_fmac_f32_e32 v95, v31, v31
	s_waitcnt lgkmcnt(0)
; __device__ __forceinline__ unsigned f2bf(float f) { unsigned u = __builtin_bit_cast(unsigned, f); return (u + 0x7fffu + ((u >> 16) & 1u)) >> 16; }
; __device__ __forceinline__ int crow(int r, int hi) { return (r & 3) + 8 * (r >> 2) + 4 * hi; }
; __device__ __forceinline__ void attn_unit(const bf16* __restrict__ Qb, const bf16* __restrict__ Kh, const bf16* __restrict__ Vh, int klat0, int nlt, int kctx0, int NT,
;                                           float lam, float post, const float* __restrict__ subw, bf16* __restrict__ Ob, char* lds) {
;     ...
;     for (int r = 0; r < 16; ++r) { const int orow = crow(r, hi_e); float v[4]; float ss = 0.f;
; #pragma unroll
;       for (int d0 = 0; d0 < 4; ++d0) { v[d0] = o[d0][r] - lam * X[(wq_e * 32 + orow) * 128 + d0 * 32 + r32_e]; ss += v[d0] * v[d0]; }
;       ss += __shfl_xor(ss, 1); ss += __shfl_xor(ss, 2); ss += __shfl_xor(ss, 4); ss += __shfl_xor(ss, 8); ss += __shfl_xor(ss, 16);
;       const float rs = 1.0f / sqrtf(ss * (1.0f / 128.0f) + LN_EPS);
; #pragma unroll
;       for (int d0 = 0; d0 < 4; ++d0) Ow[(long)orow * DM + d0 * 32 + r32_e] = (bf16)f2bf(v[d0] * rs * sw[d0]); }
	v_or_b32_e32 v245, 2, v30
	v_add_u32_e32 v244, v245, v8
	v_lshl_add_u32 v244, v244, 7, v138
	v_lshl_add_u32 v244, v244, 2, 0
	ds_read2_b32 v[236:237], v244 offset1:32
	ds_read2_b32 v[238:239], v244 offset0:64 offset1:96
	v_fma_f32 v9, -v160, v242, v93
	v_fmac_f32_e32 v95, v9, v9
	v_fma_f32 v93, -v160, v243, v94
	v_fmac_f32_e32 v95, v93, v93
	s_nop 1
	v_mov_b32_dpp v94, v95 quad_perm:[1,0,3,2] row_mask:0xf bank_mask:0xf
	v_add_f32_e32 v94, v95, v94
	s_nop 1
	v_mov_b32_dpp v95, v94 quad_perm:[2,3,0,1] row_mask:0xf bank_mask:0xf
	v_add_f32_e32 v94, v94, v95
	s_nop 1
	v_mov_b32_dpp v95, v94 row_half_mirror row_mask:0xf bank_mask:0xf
	v_add_f32_e32 v94, v94, v95
	s_nop 1
	v_mov_b32_dpp v95, v94 row_mirror row_mask:0xf bank_mask:0xf
	v_add_f32_e32 v94, v94, v95
	v_mov_b32_e32 v95, v94
	s_nop 1
	v_permlane16_swap_b32_e32 v94, v95
	v_add_f32_e32 v94, v94, v95
	v_fmamk_f32 v94, v94, 0x3c000000, v179
	v_cmp_gt_f32_e32 vcc, s4, v94
	v_mul_f32_e32 v95, 0x4f800000, v94
	s_nop 0
	v_cndmask_b32_e32 v94, v94, v95, vcc
	v_sqrt_f32_e32 v95, v94
	s_nop 0
	v_add_u32_e32 v96, -1, v95
	v_fma_f32 v97, -v96, v95, v94
	v_cmp_ge_f32_e64 s[0:1], 0, v97
	v_add_u32_e32 v97, 1, v95
	s_nop 0
	v_cndmask_b32_e64 v96, v95, v96, s[0:1]
	v_fma_f32 v95, -v97, v95, v94
	v_cmp_lt_f32_e64 s[0:1], 0, v95
	s_nop 1
	v_cndmask_b32_e64 v95, v96, v97, s[0:1]
	v_mul_f32_e32 v96, 0x37800000, v95
	v_cndmask_b32_e32 v95, v95, v96, vcc
	v_cmp_class_f32_e32 vcc, v94, v180
	s_nop 1
	v_cndmask_b32_e32 v94, v95, v94, vcc
	v_div_scale_f32 v95, s[0:1], v94, v94, 1.0
	v_rcp_f32_e32 v96, v95
	s_nop 0
	v_fma_f32 v97, -v95, v96, 1.0
	v_fmac_f32_e32 v96, v97, v96
	v_div_scale_f32 v97, vcc, 1.0, v94, 1.0
	v_mul_f32_e32 v99, v97, v96
	v_fma_f32 v100, -v95, v99, v97
	v_fmac_f32_e32 v99, v100, v96
	v_fma_f32 v95, -v95, v99, v97
	v_div_fmas_f32 v95, v95, v96, v99
	v_div_fixup_f32 v96, v95, v94, 1.0
	v_mul_f32_e32 v31, v31, v96
	v_ashrrev_i32_e32 v99, 31, v98
	v_mul_f32_e32 v31, v34, v31
	v_lshlrev_b64 v[94:95], 12, v[98:99]
	v_bfe_u32 v97, v31, 16, 1
	v_lshl_add_u64 v[94:95], v[4:5], 0, v[94:95]
	v_add3_u32 v31, v31, v97, s70
	global_store_short_d16_hi v[94:95], v31, off
	v_mul_f32_e32 v31, v88, v96
	v_mul_f32_e32 v31, v35, v31
	v_bfe_u32 v88, v31, 16, 1
	v_mul_f32_e32 v9, v9, v96
	v_add3_u32 v31, v31, v88, s70
	v_mul_f32_e32 v9, v36, v9
	global_store_short_d16_hi v[94:95], v31, off offset:64
	v_bfe_u32 v31, v9, 16, 1
	v_add3_u32 v9, v9, v31, s70
	global_store_short_d16_hi v[94:95], v9, off offset:128
	v_mul_f32_e32 v9, v93, v96
	v_mul_f32_e32 v9, v37, v9
	v_bfe_u32 v31, v9, 16, 1
	v_add3_u32 v9, v9, v31, s70
	v_or_b32_e32 v88, 2, v30
	global_store_short_d16_hi v[94:95], v9, off offset:192
	v_add_u32_e32 v9, v88, v8
	v_lshl_add_u32 v9, v9, 7, v138
	v_lshl_add_u32 v9, v9, 2, 0
	v_or_b32_e32 v30, 3, v30
	s_waitcnt lgkmcnt(1)
	v_fma_f32 v31, -v160, v236, v91
	v_fma_f32 v91, -v160, v237, v92
	v_mul_f32_e32 v94, v91, v91
	v_fmac_f32_e32 v94, v31, v31
	s_waitcnt lgkmcnt(0)
	v_add_u32_e32 v244, v30, v8
	v_lshl_add_u32 v244, v244, 7, v138
	v_lshl_add_u32 v244, v244, 2, 0
	ds_read2_b32 v[240:241], v244 offset1:32
	ds_read2_b32 v[242:243], v244 offset0:64 offset1:96
	v_fma_f32 v9, -v160, v238, v89
	v_fmac_f32_e32 v94, v9, v9
	v_fma_f32 v90, -v160, v239, v90
	v_fmac_f32_e32 v94, v90, v90
	s_nop 1
	v_mov_b32_dpp v89, v94 quad_perm:[1,0,3,2] row_mask:0xf bank_mask:0xf
	v_add_f32_e32 v89, v94, v89
	s_nop 1
	v_mov_b32_dpp v92, v89 quad_perm:[2,3,0,1] row_mask:0xf bank_mask:0xf
	v_add_f32_e32 v89, v89, v92
	s_nop 1
	v_mov_b32_dpp v92, v89 row_half_mirror row_mask:0xf bank_mask:0xf
	v_add_f32_e32 v89, v89, v92
	s_nop 1
	v_mov_b32_dpp v92, v89 row_mirror row_mask:0xf bank_mask:0xf
	v_add_f32_e32 v89, v89, v92
	v_mov_b32_e32 v92, v89
	s_nop 1
	v_permlane16_swap_b32_e32 v89, v92
	v_add_f32_e32 v89, v89, v92
	v_fmamk_f32 v89, v89, 0x3c000000, v179
	v_cmp_gt_f32_e32 vcc, s4, v89
	v_mul_f32_e32 v92, 0x4f800000, v89
	s_nop 0
	v_cndmask_b32_e32 v89, v89, v92, vcc
	v_sqrt_f32_e32 v92, v89
	s_nop 0
	v_add_u32_e32 v93, -1, v92
	v_fma_f32 v94, -v93, v92, v89
	v_cmp_ge_f32_e64 s[0:1], 0, v94
	v_add_u32_e32 v94, 1, v92
	s_nop 0
	v_cndmask_b32_e64 v93, v92, v93, s[0:1]
	v_fma_f32 v92, -v94, v92, v89
	v_cmp_lt_f32_e64 s[0:1], 0, v92
	s_nop 1
	v_cndmask_b32_e64 v92, v93, v94, s[0:1]
	v_mul_f32_e32 v93, 0x37800000, v92
	v_cndmask_b32_e32 v92, v92, v93, vcc
	v_cmp_class_f32_e32 vcc, v89, v180
	s_nop 1
	v_cndmask_b32_e32 v89, v92, v89, vcc
	v_div_scale_f32 v92, s[0:1], v89, v89, 1.0
	v_rcp_f32_e32 v93, v92
	s_nop 0
	v_fma_f32 v94, -v92, v93, 1.0
	v_fmac_f32_e32 v93, v94, v93
	v_div_scale_f32 v94, vcc, 1.0, v89, 1.0
	v_mul_f32_e32 v95, v94, v93
	v_fma_f32 v96, -v92, v95, v94
	v_fmac_f32_e32 v95, v96, v93
	v_fma_f32 v92, -v92, v95, v94
	v_div_fmas_f32 v92, v92, v93, v95
	v_div_fixup_f32 v92, v92, v89, 1.0
	v_mul_f32_e32 v31, v31, v92
	v_ashrrev_i32_e32 v89, 31, v88
	v_mul_f32_e32 v31, v34, v31
	v_lshlrev_b64 v[88:89], 12, v[88:89]
	v_bfe_u32 v93, v31, 16, 1
	v_lshl_add_u64 v[88:89], v[4:5], 0, v[88:89]
	v_add3_u32 v31, v31, v93, s70
	global_store_short_d16_hi v[88:89], v31, off
	v_mul_f32_e32 v31, v91, v92
	v_mul_f32_e32 v31, v35, v31
	v_bfe_u32 v91, v31, 16, 1
	v_mul_f32_e32 v9, v9, v92
	v_add3_u32 v31, v31, v91, s70
	v_mul_f32_e32 v9, v36, v9
	global_store_short_d16_hi v[88:89], v31, off offset:64
	v_bfe_u32 v31, v9, 16, 1
	v_add3_u32 v9, v9, v31, s70
	global_store_short_d16_hi v[88:89], v9, off offset:128
	v_mul_f32_e32 v9, v90, v92
	v_mul_f32_e32 v9, v37, v9
	v_bfe_u32 v31, v9, 16, 1
	v_add3_u32 v9, v9, v31, s70
	global_store_short_d16_hi v[88:89], v9, off offset:192
	v_add_u32_e32 v9, v30, v8
	v_lshl_add_u32 v9, v9, 7, v138
	v_lshl_add_u32 v9, v9, 2, 0
	s_waitcnt lgkmcnt(1)
; __device__ __forceinline__ unsigned f2bf(float f) { unsigned u = __builtin_bit_cast(unsigned, f); return (u + 0x7fffu + ((u >> 16) & 1u)) >> 16; }
; __device__ __forceinline__ int crow(int r, int hi) { return (r & 3) + 8 * (r >> 2) + 4 * hi; }
; __device__ __forceinline__ void attn_unit(const bf16* __restrict__ Qb, const bf16* __restrict__ Kh, const bf16* __restrict__ Vh, int klat0, int nlt, int kctx0, int NT,
;                                           float lam, float post, const float* __restrict__ subw, bf16* __restrict__ Ob, char* lds) {
;     ...
;     for (int r = 0; r < 16; ++r) { const int orow = crow(r, hi_e); float v[4]; float ss = 0.f;
; #pragma unroll
;       for (int d0 = 0; d0 < 4; ++d0) { v[d0] = o[d0][r] - lam * X[(wq_e * 32 + orow) * 128 + d0 * 32 + r32_e]; ss += v[d0] * v[d0]; }
;       ss += __shfl_xor(ss, 1); ss += __shfl_xor(ss, 2); ss += __shfl_xor(ss, 4); ss += __shfl_xor(ss, 8); ss += __shfl_xor(ss, 16);
;       const float rs = 1.0f / sqrtf(ss * (1.0f / 128.0f) + LN_EPS);
; #pragma unroll
;       for (int d0 = 0; d0 < 4; ++d0) Ow[(long)orow * DM + d0 * 32 + r32_e] = (bf16)f2bf(v[d0] * rs * sw[d0]); }
	v_fma_f32 v88, -v160, v240, v86
	v_fma_f32 v89, -v160, v241, v87
	v_mul_f32_e32 v31, v89, v89
	v_fmac_f32_e32 v31, v88, v88
	s_waitcnt lgkmcnt(0)
	v_add_u32_e32 v244, v28, v8
	v_lshl_add_u32 v244, v244, 7, v138
	v_lshl_add_u32 v244, v244, 2, 0
	ds_read2_b32 v[236:237], v244 offset1:32
	ds_read2_b32 v[238:239], v244 offset0:64 offset1:96
	v_fma_f32 v9, -v160, v242, v84
	v_fmac_f32_e32 v31, v9, v9
	v_fma_f32 v84, -v160, v243, v85
	v_fmac_f32_e32 v31, v84, v84
	s_nop 1
	v_mov_b32_dpp v85, v31 quad_perm:[1,0,3,2] row_mask:0xf bank_mask:0xf
	v_add_f32_e32 v31, v31, v85
	s_nop 1
	v_mov_b32_dpp v85, v31 quad_perm:[2,3,0,1] row_mask:0xf bank_mask:0xf
	v_add_f32_e32 v31, v31, v85
	s_nop 1
	v_mov_b32_dpp v85, v31 row_half_mirror row_mask:0xf bank_mask:0xf
	v_add_f32_e32 v31, v31, v85
	s_nop 1
	v_mov_b32_dpp v85, v31 row_mirror row_mask:0xf bank_mask:0xf
	v_add_f32_e32 v31, v31, v85
	v_mov_b32_e32 v85, v31
	s_nop 1
	v_permlane16_swap_b32_e32 v31, v85
	v_add_f32_e32 v31, v31, v85
	v_fmamk_f32 v31, v31, 0x3c000000, v179
	v_cmp_gt_f32_e32 vcc, s4, v31
	v_mul_f32_e32 v85, 0x4f800000, v31
	s_nop 0
	v_cndmask_b32_e32 v31, v31, v85, vcc
	v_sqrt_f32_e32 v85, v31
	s_nop 0
	v_add_u32_e32 v86, -1, v85
	v_fma_f32 v87, -v86, v85, v31
	v_cmp_ge_f32_e64 s[0:1], 0, v87
	v_add_u32_e32 v87, 1, v85
	s_nop 0
	v_cndmask_b32_e64 v86, v85, v86, s[0:1]
	v_fma_f32 v85, -v87, v85, v31
	v_cmp_lt_f32_e64 s[0:1], 0, v85
	s_nop 1
	v_cndmask_b32_e64 v85, v86, v87, s[0:1]
	v_mul_f32_e32 v86, 0x37800000, v85
	v_cndmask_b32_e32 v85, v85, v86, vcc
	v_cmp_class_f32_e32 vcc, v31, v180
	s_nop 1
	v_cndmask_b32_e32 v31, v85, v31, vcc
	v_div_scale_f32 v85, s[0:1], v31, v31, 1.0
	v_rcp_f32_e32 v86, v85
	s_nop 0
	v_fma_f32 v87, -v85, v86, 1.0
	v_fmac_f32_e32 v86, v87, v86
	v_div_scale_f32 v87, vcc, 1.0, v31, 1.0
	v_mul_f32_e32 v90, v87, v86
	v_fma_f32 v91, -v85, v90, v87
	v_fmac_f32_e32 v90, v91, v86
	v_fma_f32 v85, -v85, v90, v87
	v_div_fmas_f32 v85, v85, v86, v90
	v_div_fixup_f32 v85, v85, v31, 1.0
	v_mul_f32_e32 v86, v88, v85
	v_ashrrev_i32_e32 v31, 31, v30
	v_mul_f32_e32 v86, v34, v86
	v_lshlrev_b64 v[30:31], 12, v[30:31]
	v_bfe_u32 v87, v86, 16, 1
	v_lshl_add_u64 v[30:31], v[4:5], 0, v[30:31]
	v_add3_u32 v86, v86, v87, s70
	global_store_short_d16_hi v[30:31], v86, off
	v_mul_f32_e32 v86, v89, v85
	v_mul_f32_e32 v86, v35, v86
	v_bfe_u32 v87, v86, 16, 1
	v_mul_f32_e32 v9, v9, v85
	v_add3_u32 v86, v86, v87, s70
	v_mul_f32_e32 v9, v36, v9
	global_store_short_d16_hi v[30:31], v86, off offset:64
	v_bfe_u32 v86, v9, 16, 1
	v_add3_u32 v9, v9, v86, s70
	global_store_short_d16_hi v[30:31], v9, off offset:128
	v_mul_f32_e32 v9, v84, v85
	v_mul_f32_e32 v9, v37, v9
	v_bfe_u32 v84, v9, 16, 1
	v_add3_u32 v9, v9, v84, s70
	global_store_short_d16_hi v[30:31], v9, off offset:192
	v_add_u32_e32 v9, v28, v8
	v_lshl_add_u32 v9, v9, 7, v138
	v_lshl_add_u32 v9, v9, 2, 0
	v_lshlrev_b64 v[28:29], 12, v[28:29]
	v_lshl_add_u64 v[28:29], v[4:5], 0, v[28:29]
	s_waitcnt lgkmcnt(1)
	v_fma_f32 v82, -v160, v236, v82
	v_fma_f32 v83, -v160, v237, v83
	v_mul_f32_e32 v84, v83, v83
	v_fmac_f32_e32 v84, v82, v82
	s_waitcnt lgkmcnt(0)
	v_add_u32_e32 v244, v26, v8
	v_lshl_add_u32 v244, v244, 7, v138
	v_lshl_add_u32 v244, v244, 2, 0
	ds_read2_b32 v[240:241], v244 offset1:32
	ds_read2_b32 v[242:243], v244 offset0:64 offset1:96
	v_fma_f32 v9, -v160, v238, v65
	v_fmac_f32_e32 v84, v9, v9
	v_fma_f32 v30, -v160, v239, v81
	v_fmac_f32_e32 v84, v30, v30
	s_nop 1
	v_mov_b32_dpp v31, v84 quad_perm:[1,0,3,2] row_mask:0xf bank_mask:0xf
	v_add_f32_e32 v31, v84, v31
	s_nop 1
	v_mov_b32_dpp v65, v31 quad_perm:[2,3,0,1] row_mask:0xf bank_mask:0xf
	v_add_f32_e32 v31, v31, v65
	s_nop 1
	v_mov_b32_dpp v65, v31 row_half_mirror row_mask:0xf bank_mask:0xf
	v_add_f32_e32 v31, v31, v65
	s_nop 1
	v_mov_b32_dpp v65, v31 row_mirror row_mask:0xf bank_mask:0xf
	v_add_f32_e32 v31, v31, v65
	v_mov_b32_e32 v65, v31
	s_nop 1
	v_permlane16_swap_b32_e32 v31, v65
	v_add_f32_e32 v31, v31, v65
	v_fmamk_f32 v31, v31, 0x3c000000, v179
	v_cmp_gt_f32_e32 vcc, s4, v31
	v_mul_f32_e32 v65, 0x4f800000, v31
	s_nop 0
	v_cndmask_b32_e32 v31, v31, v65, vcc
	v_sqrt_f32_e32 v65, v31
	s_nop 0
	v_add_u32_e32 v81, -1, v65
	v_fma_f32 v84, -v81, v65, v31
	v_cmp_ge_f32_e64 s[0:1], 0, v84
	v_add_u32_e32 v84, 1, v65
	s_nop 0
	v_cndmask_b32_e64 v81, v65, v81, s[0:1]
	v_fma_f32 v65, -v84, v65, v31
	v_cmp_lt_f32_e64 s[0:1], 0, v65
	s_nop 1
	v_cndmask_b32_e64 v65, v81, v84, s[0:1]
	v_mul_f32_e32 v81, 0x37800000, v65
	v_cndmask_b32_e32 v65, v65, v81, vcc
	v_cmp_class_f32_e32 vcc, v31, v180
	s_nop 1
	v_cndmask_b32_e32 v31, v65, v31, vcc
	v_div_scale_f32 v65, s[0:1], v31, v31, 1.0
	v_rcp_f32_e32 v81, v65
	s_nop 0
	v_fma_f32 v84, -v65, v81, 1.0
	v_fmac_f32_e32 v81, v84, v81
	v_div_scale_f32 v84, vcc, 1.0, v31, 1.0
	v_mul_f32_e32 v85, v84, v81
	v_fma_f32 v86, -v65, v85, v84
	v_fmac_f32_e32 v85, v86, v81
	v_fma_f32 v65, -v65, v85, v84
	v_div_fmas_f32 v65, v65, v81, v85
	v_div_fixup_f32 v31, v65, v31, 1.0
	v_mul_f32_e32 v65, v82, v31
	v_mul_f32_e32 v65, v34, v65
	v_bfe_u32 v81, v65, 16, 1
	v_add3_u32 v65, v65, v81, s70
	global_store_short_d16_hi v[28:29], v65, off
	v_mul_f32_e32 v65, v83, v31
	v_mul_f32_e32 v65, v35, v65
	v_bfe_u32 v81, v65, 16, 1
	v_mul_f32_e32 v9, v9, v31
	v_add3_u32 v65, v65, v81, s70
	v_mul_f32_e32 v9, v36, v9
	global_store_short_d16_hi v[28:29], v65, off offset:64
	v_bfe_u32 v65, v9, 16, 1
	v_add3_u32 v9, v9, v65, s70
	global_store_short_d16_hi v[28:29], v9, off offset:128
	v_mul_f32_e32 v9, v30, v31
	v_mul_f32_e32 v9, v37, v9
	v_bfe_u32 v30, v9, 16, 1
	v_add3_u32 v9, v9, v30, s70
	global_store_short_d16_hi v[28:29], v9, off offset:192
	v_add_u32_e32 v9, v26, v8
	v_lshl_add_u32 v9, v9, 7, v138
	v_lshl_add_u32 v9, v9, 2, 0
	v_lshlrev_b64 v[26:27], 12, v[26:27]
	v_lshl_add_u64 v[26:27], v[4:5], 0, v[26:27]
	s_waitcnt lgkmcnt(1)
; __device__ __forceinline__ unsigned f2bf(float f) { unsigned u = __builtin_bit_cast(unsigned, f); return (u + 0x7fffu + ((u >> 16) & 1u)) >> 16; }
; __device__ __forceinline__ int crow(int r, int hi) { return (r & 3) + 8 * (r >> 2) + 4 * hi; }
; __device__ __forceinline__ void attn_unit(const bf16* __restrict__ Qb, const bf16* __restrict__ Kh, const bf16* __restrict__ Vh, int klat0, int nlt, int kctx0, int NT,
;                                           float lam, float post, const float* __restrict__ subw, bf16* __restrict__ Ob, char* lds) {
;     ...
;     for (int r = 0; r < 16; ++r) { const int orow = crow(r, hi_e); float v[4]; float ss = 0.f;
; #pragma unroll
;       for (int d0 = 0; d0 < 4; ++d0) { v[d0] = o[d0][r] - lam * X[(wq_e * 32 + orow) * 128 + d0 * 32 + r32_e]; ss += v[d0] * v[d0]; }
;       ss += __shfl_xor(ss, 1); ss += __shfl_xor(ss, 2); ss += __shfl_xor(ss, 4); ss += __shfl_xor(ss, 8); ss += __shfl_xor(ss, 16);
;       const float rs = 1.0f / sqrtf(ss * (1.0f / 128.0f) + LN_EPS);
; #pragma unroll
;       for (int d0 = 0; d0 < 4; ++d0) Ow[(long)orow * DM + d0 * 32 + r32_e] = (bf16)f2bf(v[d0] * rs * sw[d0]); }
	v_fma_f32 v30, -v160, v240, v79
	v_fma_f32 v31, -v160, v241, v80
	v_mul_f32_e32 v65, v31, v31
	v_fmac_f32_e32 v65, v30, v30
	s_waitcnt lgkmcnt(0)
	v_add_u32_e32 v244, v24, v8
	v_lshl_add_u32 v244, v244, 7, v138
	v_lshl_add_u32 v244, v244, 2, 0
	ds_read2_b32 v[236:237], v244 offset1:32
	ds_read2_b32 v[238:239], v244 offset0:64 offset1:96
	v_fma_f32 v9, -v160, v242, v63
	v_fmac_f32_e32 v65, v9, v9
	v_fma_f32 v28, -v160, v243, v64
	v_fmac_f32_e32 v65, v28, v28
	s_nop 1
	v_mov_b32_dpp v29, v65 quad_perm:[1,0,3,2] row_mask:0xf bank_mask:0xf
	v_add_f32_e32 v29, v65, v29
	s_nop 1
	v_mov_b32_dpp v63, v29 quad_perm:[2,3,0,1] row_mask:0xf bank_mask:0xf
	v_add_f32_e32 v29, v29, v63
	s_nop 1
	v_mov_b32_dpp v63, v29 row_half_mirror row_mask:0xf bank_mask:0xf
	v_add_f32_e32 v29, v29, v63
	s_nop 1
	v_mov_b32_dpp v63, v29 row_mirror row_mask:0xf bank_mask:0xf
	v_add_f32_e32 v29, v29, v63
	v_mov_b32_e32 v63, v29
	s_nop 1
	v_permlane16_swap_b32_e32 v29, v63
	v_add_f32_e32 v29, v29, v63
	v_fmamk_f32 v29, v29, 0x3c000000, v179
	v_cmp_gt_f32_e32 vcc, s4, v29
	v_mul_f32_e32 v63, 0x4f800000, v29
	s_nop 0
	v_cndmask_b32_e32 v29, v29, v63, vcc
	v_sqrt_f32_e32 v63, v29
	s_nop 0
	v_add_u32_e32 v64, -1, v63
	v_fma_f32 v65, -v64, v63, v29
	v_cmp_ge_f32_e64 s[0:1], 0, v65
	v_add_u32_e32 v65, 1, v63
	s_nop 0
	v_cndmask_b32_e64 v64, v63, v64, s[0:1]
	v_fma_f32 v63, -v65, v63, v29
	v_cmp_lt_f32_e64 s[0:1], 0, v63
	s_nop 1
	v_cndmask_b32_e64 v63, v64, v65, s[0:1]
	v_mul_f32_e32 v64, 0x37800000, v63
	v_cndmask_b32_e32 v63, v63, v64, vcc
	v_cmp_class_f32_e32 vcc, v29, v180
	s_nop 1
	v_cndmask_b32_e32 v29, v63, v29, vcc
	v_div_scale_f32 v63, s[0:1], v29, v29, 1.0
	v_rcp_f32_e32 v64, v63
	s_nop 0
	v_fma_f32 v65, -v63, v64, 1.0
	v_fmac_f32_e32 v64, v65, v64
	v_div_scale_f32 v65, vcc, 1.0, v29, 1.0
	v_mul_f32_e32 v79, v65, v64
	v_fma_f32 v80, -v63, v79, v65
	v_fmac_f32_e32 v79, v80, v64
	v_fma_f32 v63, -v63, v79, v65
	v_div_fmas_f32 v63, v63, v64, v79
	v_div_fixup_f32 v29, v63, v29, 1.0
	v_mul_f32_e32 v30, v30, v29
	v_mul_f32_e32 v30, v34, v30
	v_bfe_u32 v63, v30, 16, 1
	v_add3_u32 v30, v30, v63, s70
	global_store_short_d16_hi v[26:27], v30, off
	v_mul_f32_e32 v30, v31, v29
	v_mul_f32_e32 v30, v35, v30
	v_bfe_u32 v31, v30, 16, 1
	v_mul_f32_e32 v9, v9, v29
	v_add3_u32 v30, v30, v31, s70
	v_mul_f32_e32 v9, v36, v9
	global_store_short_d16_hi v[26:27], v30, off offset:64
	v_bfe_u32 v30, v9, 16, 1
	v_add3_u32 v9, v9, v30, s70
	global_store_short_d16_hi v[26:27], v9, off offset:128
	v_mul_f32_e32 v9, v28, v29
	v_mul_f32_e32 v9, v37, v9
	v_bfe_u32 v28, v9, 16, 1
	v_add3_u32 v9, v9, v28, s70
	global_store_short_d16_hi v[26:27], v9, off offset:192
	v_add_u32_e32 v9, v24, v8
	v_lshl_add_u32 v9, v9, 7, v138
	v_lshl_add_u32 v9, v9, 2, 0
	v_lshlrev_b64 v[24:25], 12, v[24:25]
	v_lshl_add_u64 v[24:25], v[4:5], 0, v[24:25]
	s_waitcnt lgkmcnt(1)
	v_fma_f32 v28, -v160, v236, v77
	v_fma_f32 v29, -v160, v237, v78
	v_mul_f32_e32 v30, v29, v29
	v_fmac_f32_e32 v30, v28, v28
	s_waitcnt lgkmcnt(0)
	v_add_u32_e32 v244, v22, v8
	v_lshl_add_u32 v244, v244, 7, v138
	v_lshl_add_u32 v244, v244, 2, 0
	ds_read2_b32 v[240:241], v244 offset1:32
	ds_read2_b32 v[242:243], v244 offset0:64 offset1:96
	v_fma_f32 v9, -v160, v238, v61
	v_fmac_f32_e32 v30, v9, v9
	v_fma_f32 v26, -v160, v239, v62
	v_fmac_f32_e32 v30, v26, v26
	s_nop 1
	v_mov_b32_dpp v27, v30 quad_perm:[1,0,3,2] row_mask:0xf bank_mask:0xf
	v_add_f32_e32 v27, v30, v27
	s_nop 1
	v_mov_b32_dpp v30, v27 quad_perm:[2,3,0,1] row_mask:0xf bank_mask:0xf
	v_add_f32_e32 v27, v27, v30
	s_nop 1
	v_mov_b32_dpp v30, v27 row_half_mirror row_mask:0xf bank_mask:0xf
	v_add_f32_e32 v27, v27, v30
	s_nop 1
	v_mov_b32_dpp v30, v27 row_mirror row_mask:0xf bank_mask:0xf
	v_add_f32_e32 v27, v27, v30
	v_mov_b32_e32 v30, v27
	s_nop 1
	v_permlane16_swap_b32_e32 v27, v30
	v_add_f32_e32 v27, v27, v30
	v_fmamk_f32 v27, v27, 0x3c000000, v179
	v_cmp_gt_f32_e32 vcc, s4, v27
	v_mul_f32_e32 v30, 0x4f800000, v27
	s_nop 0
	v_cndmask_b32_e32 v27, v27, v30, vcc
	v_sqrt_f32_e32 v30, v27
	s_nop 0
	v_add_u32_e32 v31, -1, v30
	v_fma_f32 v61, -v31, v30, v27
	v_cmp_ge_f32_e64 s[0:1], 0, v61
	v_add_u32_e32 v61, 1, v30
	s_nop 0
	v_cndmask_b32_e64 v31, v30, v31, s[0:1]
	v_fma_f32 v30, -v61, v30, v27
	v_cmp_lt_f32_e64 s[0:1], 0, v30
	s_nop 1
	v_cndmask_b32_e64 v30, v31, v61, s[0:1]
	v_mul_f32_e32 v31, 0x37800000, v30
	v_cndmask_b32_e32 v30, v30, v31, vcc
	v_cmp_class_f32_e32 vcc, v27, v180
	s_nop 1
	v_cndmask_b32_e32 v27, v30, v27, vcc
	v_div_scale_f32 v30, s[0:1], v27, v27, 1.0
	v_rcp_f32_e32 v31, v30
	s_nop 0
	v_fma_f32 v61, -v30, v31, 1.0
	v_fmac_f32_e32 v31, v61, v31
	v_div_scale_f32 v61, vcc, 1.0, v27, 1.0
	v_mul_f32_e32 v62, v61, v31
	v_fma_f32 v63, -v30, v62, v61
	v_fmac_f32_e32 v62, v63, v31
	v_fma_f32 v30, -v30, v62, v61
	v_div_fmas_f32 v30, v30, v31, v62
	v_div_fixup_f32 v27, v30, v27, 1.0
	v_mul_f32_e32 v28, v28, v27
	v_mul_f32_e32 v28, v34, v28
	v_bfe_u32 v30, v28, 16, 1
	v_add3_u32 v28, v28, v30, s70
	global_store_short_d16_hi v[24:25], v28, off
	v_mul_f32_e32 v28, v29, v27
	v_mul_f32_e32 v28, v35, v28
	v_bfe_u32 v29, v28, 16, 1
	v_mul_f32_e32 v9, v9, v27
	v_add3_u32 v28, v28, v29, s70
	v_mul_f32_e32 v9, v36, v9
	global_store_short_d16_hi v[24:25], v28, off offset:64
	v_bfe_u32 v28, v9, 16, 1
	v_add3_u32 v9, v9, v28, s70
	global_store_short_d16_hi v[24:25], v9, off offset:128
	v_mul_f32_e32 v9, v26, v27
	v_mul_f32_e32 v9, v37, v9
	v_bfe_u32 v26, v9, 16, 1
	v_add3_u32 v9, v9, v26, s70
	global_store_short_d16_hi v[24:25], v9, off offset:192
	v_add_u32_e32 v9, v22, v8
	v_lshl_add_u32 v9, v9, 7, v138
	v_lshl_add_u32 v9, v9, 2, 0
	v_lshlrev_b64 v[22:23], 12, v[22:23]
	v_lshl_add_u64 v[22:23], v[4:5], 0, v[22:23]
	s_waitcnt lgkmcnt(1)
; __device__ __forceinline__ unsigned f2bf(float f) { unsigned u = __builtin_bit_cast(unsigned, f); return (u + 0x7fffu + ((u >> 16) & 1u)) >> 16; }
; __device__ __forceinline__ int crow(int r, int hi) { return (r & 3) + 8 * (r >> 2) + 4 * hi; }
; __device__ __forceinline__ void attn_unit(const bf16* __restrict__ Qb, const bf16* __restrict__ Kh, const bf16* __restrict__ Vh, int klat0, int nlt, int kctx0, int NT,
;                                           float lam, float post, const float* __restrict__ subw, bf16* __restrict__ Ob, char* lds) {
;     ...
;     for (int r = 0; r < 16; ++r) { const int orow = crow(r, hi_e); float v[4]; float ss = 0.f;
; #pragma unroll
;       for (int d0 = 0; d0 < 4; ++d0) { v[d0] = o[d0][r] - lam * X[(wq_e * 32 + orow) * 128 + d0 * 32 + r32_e]; ss += v[d0] * v[d0]; }
;       ss += __shfl_xor(ss, 1); ss += __shfl_xor(ss, 2); ss += __shfl_xor(ss, 4); ss += __shfl_xor(ss, 8); ss += __shfl_xor(ss, 16);
;       const float rs = 1.0f / sqrtf(ss * (1.0f / 128.0f) + LN_EPS);
; #pragma unroll
;       for (int d0 = 0; d0 < 4; ++d0) Ow[(long)orow * DM + d0 * 32 + r32_e] = (bf16)f2bf(v[d0] * rs * sw[d0]); }
	v_fma_f32 v26, -v160, v240, v75
	v_fma_f32 v27, -v160, v241, v76
	v_mul_f32_e32 v28, v27, v27
	v_fmac_f32_e32 v28, v26, v26
	s_waitcnt lgkmcnt(0)
	v_add_u32_e32 v244, v20, v8
	v_lshl_add_u32 v244, v244, 7, v138
	v_lshl_add_u32 v244, v244, 2, 0
	ds_read2_b32 v[236:237], v244 offset1:32
	ds_read2_b32 v[238:239], v244 offset0:64 offset1:96
	v_fma_f32 v9, -v160, v242, v60
	v_fmac_f32_e32 v28, v9, v9
	v_fma_f32 v24, -v160, v243, v49
	v_fmac_f32_e32 v28, v24, v24
	s_nop 1
	v_mov_b32_dpp v25, v28 quad_perm:[1,0,3,2] row_mask:0xf bank_mask:0xf
	v_add_f32_e32 v25, v28, v25
	s_nop 1
	v_mov_b32_dpp v28, v25 quad_perm:[2,3,0,1] row_mask:0xf bank_mask:0xf
	v_add_f32_e32 v25, v25, v28
	s_nop 1
	v_mov_b32_dpp v28, v25 row_half_mirror row_mask:0xf bank_mask:0xf
	v_add_f32_e32 v25, v25, v28
	s_nop 1
	v_mov_b32_dpp v28, v25 row_mirror row_mask:0xf bank_mask:0xf
	v_add_f32_e32 v25, v25, v28
	v_mov_b32_e32 v28, v25
	s_nop 1
	v_permlane16_swap_b32_e32 v25, v28
	v_add_f32_e32 v25, v25, v28
	v_fmamk_f32 v25, v25, 0x3c000000, v179
	v_cmp_gt_f32_e32 vcc, s4, v25
	v_mul_f32_e32 v28, 0x4f800000, v25
	s_nop 0
	v_cndmask_b32_e32 v25, v25, v28, vcc
	v_sqrt_f32_e32 v28, v25
	s_nop 0
	v_add_u32_e32 v29, -1, v28
	v_fma_f32 v30, -v29, v28, v25
	v_cmp_ge_f32_e64 s[0:1], 0, v30
	v_add_u32_e32 v30, 1, v28
	s_nop 0
	v_cndmask_b32_e64 v29, v28, v29, s[0:1]
	v_fma_f32 v28, -v30, v28, v25
	v_cmp_lt_f32_e64 s[0:1], 0, v28
	s_nop 1
	v_cndmask_b32_e64 v28, v29, v30, s[0:1]
	v_mul_f32_e32 v29, 0x37800000, v28
	v_cndmask_b32_e32 v28, v28, v29, vcc
	v_cmp_class_f32_e32 vcc, v25, v180
	s_nop 1
	v_cndmask_b32_e32 v25, v28, v25, vcc
	v_div_scale_f32 v28, s[0:1], v25, v25, 1.0
	v_rcp_f32_e32 v29, v28
	s_nop 0
	v_fma_f32 v30, -v28, v29, 1.0
	v_fmac_f32_e32 v29, v30, v29
	v_div_scale_f32 v30, vcc, 1.0, v25, 1.0
	v_mul_f32_e32 v31, v30, v29
	v_fma_f32 v49, -v28, v31, v30
	v_fmac_f32_e32 v31, v49, v29
	v_fma_f32 v28, -v28, v31, v30
	v_div_fmas_f32 v28, v28, v29, v31
	v_div_fixup_f32 v25, v28, v25, 1.0
	v_mul_f32_e32 v26, v26, v25
	v_mul_f32_e32 v26, v34, v26
	v_bfe_u32 v28, v26, 16, 1
	v_add3_u32 v26, v26, v28, s70
	global_store_short_d16_hi v[22:23], v26, off
	v_mul_f32_e32 v26, v27, v25
	v_mul_f32_e32 v26, v35, v26
	v_bfe_u32 v27, v26, 16, 1
	v_mul_f32_e32 v9, v9, v25
	v_add3_u32 v26, v26, v27, s70
	v_mul_f32_e32 v9, v36, v9
	global_store_short_d16_hi v[22:23], v26, off offset:64
	v_bfe_u32 v26, v9, 16, 1
	v_add3_u32 v9, v9, v26, s70
	global_store_short_d16_hi v[22:23], v9, off offset:128
	v_mul_f32_e32 v9, v24, v25
	v_mul_f32_e32 v9, v37, v9
	v_bfe_u32 v24, v9, 16, 1
	v_add3_u32 v9, v9, v24, s70
	global_store_short_d16_hi v[22:23], v9, off offset:192
	v_add_u32_e32 v9, v20, v8
	v_lshl_add_u32 v9, v9, 7, v138
	v_lshl_add_u32 v9, v9, 2, 0
	v_lshlrev_b64 v[20:21], 12, v[20:21]
	v_lshl_add_u64 v[20:21], v[4:5], 0, v[20:21]
	s_waitcnt lgkmcnt(1)
	v_fma_f32 v24, -v160, v236, v73
	v_fma_f32 v25, -v160, v237, v74
	v_mul_f32_e32 v26, v25, v25
	v_fmac_f32_e32 v26, v24, v24
	s_waitcnt lgkmcnt(0)
	v_add_u32_e32 v244, v18, v8
	v_lshl_add_u32 v244, v244, 7, v138
	v_lshl_add_u32 v244, v244, 2, 0
	ds_read2_b32 v[240:241], v244 offset1:32
	ds_read2_b32 v[242:243], v244 offset0:64 offset1:96
	v_fma_f32 v9, -v160, v238, v59
	v_fmac_f32_e32 v26, v9, v9
	v_fma_f32 v22, -v160, v239, v48
	v_fmac_f32_e32 v26, v22, v22
	s_nop 1
	v_mov_b32_dpp v23, v26 quad_perm:[1,0,3,2] row_mask:0xf bank_mask:0xf
	v_add_f32_e32 v23, v26, v23
	s_nop 1
	v_mov_b32_dpp v26, v23 quad_perm:[2,3,0,1] row_mask:0xf bank_mask:0xf
	v_add_f32_e32 v23, v23, v26
	s_nop 1
	v_mov_b32_dpp v26, v23 row_half_mirror row_mask:0xf bank_mask:0xf
	v_add_f32_e32 v23, v23, v26
	s_nop 1
	v_mov_b32_dpp v26, v23 row_mirror row_mask:0xf bank_mask:0xf
	v_add_f32_e32 v23, v23, v26
	v_mov_b32_e32 v26, v23
	s_nop 1
	v_permlane16_swap_b32_e32 v23, v26
	v_add_f32_e32 v23, v23, v26
	v_fmamk_f32 v23, v23, 0x3c000000, v179
	v_cmp_gt_f32_e32 vcc, s4, v23
	v_mul_f32_e32 v26, 0x4f800000, v23
	s_nop 0
	v_cndmask_b32_e32 v23, v23, v26, vcc
	v_sqrt_f32_e32 v26, v23
	s_nop 0
	v_add_u32_e32 v27, -1, v26
	v_fma_f32 v28, -v27, v26, v23
	v_cmp_ge_f32_e64 s[0:1], 0, v28
	v_add_u32_e32 v28, 1, v26
	s_nop 0
	v_cndmask_b32_e64 v27, v26, v27, s[0:1]
	v_fma_f32 v26, -v28, v26, v23
	v_cmp_lt_f32_e64 s[0:1], 0, v26
	s_nop 1
	v_cndmask_b32_e64 v26, v27, v28, s[0:1]
	v_mul_f32_e32 v27, 0x37800000, v26
	v_cndmask_b32_e32 v26, v26, v27, vcc
	v_cmp_class_f32_e32 vcc, v23, v180
	s_nop 1
	v_cndmask_b32_e32 v23, v26, v23, vcc
	v_div_scale_f32 v26, s[0:1], v23, v23, 1.0
	v_rcp_f32_e32 v27, v26
	s_nop 0
	v_fma_f32 v28, -v26, v27, 1.0
	v_fmac_f32_e32 v27, v28, v27
	v_div_scale_f32 v28, vcc, 1.0, v23, 1.0
	v_mul_f32_e32 v29, v28, v27
	v_fma_f32 v30, -v26, v29, v28
	v_fmac_f32_e32 v29, v30, v27
	v_fma_f32 v26, -v26, v29, v28
	v_div_fmas_f32 v26, v26, v27, v29
	v_div_fixup_f32 v23, v26, v23, 1.0
	v_mul_f32_e32 v24, v24, v23
	v_mul_f32_e32 v24, v34, v24
	v_bfe_u32 v26, v24, 16, 1
	v_add3_u32 v24, v24, v26, s70
	global_store_short_d16_hi v[20:21], v24, off
	v_mul_f32_e32 v24, v25, v23
	v_mul_f32_e32 v24, v35, v24
	v_bfe_u32 v25, v24, 16, 1
	v_mul_f32_e32 v9, v9, v23
	v_add3_u32 v24, v24, v25, s70
	v_mul_f32_e32 v9, v36, v9
	global_store_short_d16_hi v[20:21], v24, off offset:64
	v_bfe_u32 v24, v9, 16, 1
	v_add3_u32 v9, v9, v24, s70
	global_store_short_d16_hi v[20:21], v9, off offset:128
	v_mul_f32_e32 v9, v22, v23
	v_mul_f32_e32 v9, v37, v9
	v_bfe_u32 v22, v9, 16, 1
	v_add3_u32 v9, v9, v22, s70
	global_store_short_d16_hi v[20:21], v9, off offset:192
	v_add_u32_e32 v9, v18, v8
	v_lshl_add_u32 v9, v9, 7, v138
	v_lshl_add_u32 v9, v9, 2, 0
	v_lshlrev_b64 v[18:19], 12, v[18:19]
	v_lshl_add_u64 v[18:19], v[4:5], 0, v[18:19]
	s_waitcnt lgkmcnt(1)
; __device__ __forceinline__ unsigned f2bf(float f) { unsigned u = __builtin_bit_cast(unsigned, f); return (u + 0x7fffu + ((u >> 16) & 1u)) >> 16; }
; __device__ __forceinline__ int crow(int r, int hi) { return (r & 3) + 8 * (r >> 2) + 4 * hi; }
; __device__ __forceinline__ void attn_unit(const bf16* __restrict__ Qb, const bf16* __restrict__ Kh, const bf16* __restrict__ Vh, int klat0, int nlt, int kctx0, int NT,
;                                           float lam, float post, const float* __restrict__ subw, bf16* __restrict__ Ob, char* lds) {
;     ...
;     for (int r = 0; r < 16; ++r) { const int orow = crow(r, hi_e); float v[4]; float ss = 0.f;
; #pragma unroll
;       for (int d0 = 0; d0 < 4; ++d0) { v[d0] = o[d0][r] - lam * X[(wq_e * 32 + orow) * 128 + d0 * 32 + r32_e]; ss += v[d0] * v[d0]; }
;       ss += __shfl_xor(ss, 1); ss += __shfl_xor(ss, 2); ss += __shfl_xor(ss, 4); ss += __shfl_xor(ss, 8); ss += __shfl_xor(ss, 16);
;       const float rs = 1.0f / sqrtf(ss * (1.0f / 128.0f) + LN_EPS);
; #pragma unroll
;       for (int d0 = 0; d0 < 4; ++d0) Ow[(long)orow * DM + d0 * 32 + r32_e] = (bf16)f2bf(v[d0] * rs * sw[d0]); }
	v_fma_f32 v22, -v160, v240, v72
	v_fma_f32 v23, -v160, v241, v58
	v_mul_f32_e32 v24, v23, v23
	v_fmac_f32_e32 v24, v22, v22
	s_waitcnt lgkmcnt(0)
	v_add_u32_e32 v244, v16, v8
	v_lshl_add_u32 v244, v244, 7, v138
	v_lshl_add_u32 v244, v244, 2, 0
	ds_read2_b32 v[236:237], v244 offset1:32
	ds_read2_b32 v[238:239], v244 offset0:64 offset1:96
	v_fma_f32 v9, -v160, v242, v57
	v_fmac_f32_e32 v24, v9, v9
	v_fma_f32 v20, -v160, v243, v47
	v_fmac_f32_e32 v24, v20, v20
	s_nop 1
	v_mov_b32_dpp v21, v24 quad_perm:[1,0,3,2] row_mask:0xf bank_mask:0xf
	v_add_f32_e32 v21, v24, v21
	s_nop 1
	v_mov_b32_dpp v24, v21 quad_perm:[2,3,0,1] row_mask:0xf bank_mask:0xf
	v_add_f32_e32 v21, v21, v24
	s_nop 1
	v_mov_b32_dpp v24, v21 row_half_mirror row_mask:0xf bank_mask:0xf
	v_add_f32_e32 v21, v21, v24
	s_nop 1
	v_mov_b32_dpp v24, v21 row_mirror row_mask:0xf bank_mask:0xf
	v_add_f32_e32 v21, v21, v24
	v_mov_b32_e32 v24, v21
	s_nop 1
	v_permlane16_swap_b32_e32 v21, v24
	v_add_f32_e32 v21, v21, v24
	v_fmamk_f32 v21, v21, 0x3c000000, v179
	v_cmp_gt_f32_e32 vcc, s4, v21
	v_mul_f32_e32 v24, 0x4f800000, v21
	s_nop 0
	v_cndmask_b32_e32 v21, v21, v24, vcc
	v_sqrt_f32_e32 v24, v21
	s_nop 0
	v_add_u32_e32 v25, -1, v24
	v_fma_f32 v26, -v25, v24, v21
	v_cmp_ge_f32_e64 s[0:1], 0, v26
	v_add_u32_e32 v26, 1, v24
	s_nop 0
	v_cndmask_b32_e64 v25, v24, v25, s[0:1]
	v_fma_f32 v24, -v26, v24, v21
	v_cmp_lt_f32_e64 s[0:1], 0, v24
	s_nop 1
	v_cndmask_b32_e64 v24, v25, v26, s[0:1]
	v_mul_f32_e32 v25, 0x37800000, v24
	v_cndmask_b32_e32 v24, v24, v25, vcc
	v_cmp_class_f32_e32 vcc, v21, v180
	s_nop 1
	v_cndmask_b32_e32 v21, v24, v21, vcc
	v_div_scale_f32 v24, s[0:1], v21, v21, 1.0
	v_rcp_f32_e32 v25, v24
	s_nop 0
	v_fma_f32 v26, -v24, v25, 1.0
	v_fmac_f32_e32 v25, v26, v25
	v_div_scale_f32 v26, vcc, 1.0, v21, 1.0
	v_mul_f32_e32 v27, v26, v25
	v_fma_f32 v28, -v24, v27, v26
	v_fmac_f32_e32 v27, v28, v25
	v_fma_f32 v24, -v24, v27, v26
	v_div_fmas_f32 v24, v24, v25, v27
	v_div_fixup_f32 v21, v24, v21, 1.0
	v_mul_f32_e32 v22, v22, v21
	v_mul_f32_e32 v22, v34, v22
	v_bfe_u32 v24, v22, 16, 1
	v_add3_u32 v22, v22, v24, s70
	global_store_short_d16_hi v[18:19], v22, off
	v_mul_f32_e32 v22, v23, v21
	v_mul_f32_e32 v22, v35, v22
	v_bfe_u32 v23, v22, 16, 1
	v_mul_f32_e32 v9, v9, v21
	v_add3_u32 v22, v22, v23, s70
	v_mul_f32_e32 v9, v36, v9
	global_store_short_d16_hi v[18:19], v22, off offset:64
	v_bfe_u32 v22, v9, 16, 1
	v_add3_u32 v9, v9, v22, s70
	global_store_short_d16_hi v[18:19], v9, off offset:128
	v_mul_f32_e32 v9, v20, v21
	v_mul_f32_e32 v9, v37, v9
	v_bfe_u32 v20, v9, 16, 1
	v_add3_u32 v9, v9, v20, s70
	global_store_short_d16_hi v[18:19], v9, off offset:192
	v_add_u32_e32 v9, v16, v8
	v_lshl_add_u32 v9, v9, 7, v138
	v_lshl_add_u32 v9, v9, 2, 0
	v_lshlrev_b64 v[16:17], 12, v[16:17]
	v_lshl_add_u64 v[16:17], v[4:5], 0, v[16:17]
	s_waitcnt lgkmcnt(1)
	v_fma_f32 v20, -v160, v236, v71
	v_fma_f32 v21, -v160, v237, v56
	v_mul_f32_e32 v22, v21, v21
	v_fmac_f32_e32 v22, v20, v20
	s_waitcnt lgkmcnt(0)
	v_add_u32_e32 v244, v14, v8
	v_lshl_add_u32 v244, v244, 7, v138
	v_lshl_add_u32 v244, v244, 2, 0
	ds_read2_b32 v[240:241], v244 offset1:32
	ds_read2_b32 v[242:243], v244 offset0:64 offset1:96
	v_fma_f32 v9, -v160, v238, v55
	v_fmac_f32_e32 v22, v9, v9
	v_fma_f32 v18, -v160, v239, v46
	v_fmac_f32_e32 v22, v18, v18
	s_nop 1
	v_mov_b32_dpp v19, v22 quad_perm:[1,0,3,2] row_mask:0xf bank_mask:0xf
	v_add_f32_e32 v19, v22, v19
	s_nop 1
	v_mov_b32_dpp v22, v19 quad_perm:[2,3,0,1] row_mask:0xf bank_mask:0xf
	v_add_f32_e32 v19, v19, v22
	s_nop 1
	v_mov_b32_dpp v22, v19 row_half_mirror row_mask:0xf bank_mask:0xf
	v_add_f32_e32 v19, v19, v22
	s_nop 1
	v_mov_b32_dpp v22, v19 row_mirror row_mask:0xf bank_mask:0xf
	v_add_f32_e32 v19, v19, v22
	v_mov_b32_e32 v22, v19
	s_nop 1
	v_permlane16_swap_b32_e32 v19, v22
	v_add_f32_e32 v19, v19, v22
	v_fmamk_f32 v19, v19, 0x3c000000, v179
	v_cmp_gt_f32_e32 vcc, s4, v19
	v_mul_f32_e32 v22, 0x4f800000, v19
	s_nop 0
	v_cndmask_b32_e32 v19, v19, v22, vcc
	v_sqrt_f32_e32 v22, v19
	s_nop 0
	v_add_u32_e32 v23, -1, v22
	v_fma_f32 v24, -v23, v22, v19
	v_cmp_ge_f32_e64 s[0:1], 0, v24
	v_add_u32_e32 v24, 1, v22
	s_nop 0
	v_cndmask_b32_e64 v23, v22, v23, s[0:1]
	v_fma_f32 v22, -v24, v22, v19
	v_cmp_lt_f32_e64 s[0:1], 0, v22
	s_nop 1
	v_cndmask_b32_e64 v22, v23, v24, s[0:1]
	v_mul_f32_e32 v23, 0x37800000, v22
	v_cndmask_b32_e32 v22, v22, v23, vcc
	v_cmp_class_f32_e32 vcc, v19, v180
	s_nop 1
	v_cndmask_b32_e32 v19, v22, v19, vcc
	v_div_scale_f32 v22, s[0:1], v19, v19, 1.0
	v_rcp_f32_e32 v23, v22
	s_nop 0
	v_fma_f32 v24, -v22, v23, 1.0
	v_fmac_f32_e32 v23, v24, v23
	v_div_scale_f32 v24, vcc, 1.0, v19, 1.0
	v_mul_f32_e32 v25, v24, v23
	v_fma_f32 v26, -v22, v25, v24
	v_fmac_f32_e32 v25, v26, v23
	v_fma_f32 v22, -v22, v25, v24
	v_div_fmas_f32 v22, v22, v23, v25
	v_div_fixup_f32 v19, v22, v19, 1.0
	v_mul_f32_e32 v20, v20, v19
	v_mul_f32_e32 v20, v34, v20
	v_bfe_u32 v22, v20, 16, 1
	v_add3_u32 v20, v20, v22, s70
	global_store_short_d16_hi v[16:17], v20, off
	v_mul_f32_e32 v20, v21, v19
	v_mul_f32_e32 v20, v35, v20
	v_bfe_u32 v21, v20, 16, 1
	v_mul_f32_e32 v9, v9, v19
	v_add3_u32 v20, v20, v21, s70
	v_mul_f32_e32 v9, v36, v9
	global_store_short_d16_hi v[16:17], v20, off offset:64
	v_bfe_u32 v20, v9, 16, 1
	v_add3_u32 v9, v9, v20, s70
	global_store_short_d16_hi v[16:17], v9, off offset:128
	v_mul_f32_e32 v9, v18, v19
	v_mul_f32_e32 v9, v37, v9
	v_bfe_u32 v18, v9, 16, 1
	v_add3_u32 v9, v9, v18, s70
	global_store_short_d16_hi v[16:17], v9, off offset:192
	v_add_u32_e32 v9, v14, v8
	v_lshl_add_u32 v9, v9, 7, v138
	v_lshl_add_u32 v9, v9, 2, 0
	v_lshlrev_b64 v[14:15], 12, v[14:15]
	v_lshl_add_u64 v[14:15], v[4:5], 0, v[14:15]
	s_waitcnt lgkmcnt(1)
; __device__ __forceinline__ unsigned f2bf(float f) { unsigned u = __builtin_bit_cast(unsigned, f); return (u + 0x7fffu + ((u >> 16) & 1u)) >> 16; }
; __device__ __forceinline__ int crow(int r, int hi) { return (r & 3) + 8 * (r >> 2) + 4 * hi; }
; __device__ __forceinline__ void attn_unit(const bf16* __restrict__ Qb, const bf16* __restrict__ Kh, const bf16* __restrict__ Vh, int klat0, int nlt, int kctx0, int NT,
;                                           float lam, float post, const float* __restrict__ subw, bf16* __restrict__ Ob, char* lds) {
;     ...
;     for (int r = 0; r < 16; ++r) { const int orow = crow(r, hi_e); float v[4]; float ss = 0.f;
; #pragma unroll
;       for (int d0 = 0; d0 < 4; ++d0) { v[d0] = o[d0][r] - lam * X[(wq_e * 32 + orow) * 128 + d0 * 32 + r32_e]; ss += v[d0] * v[d0]; }
;       ss += __shfl_xor(ss, 1); ss += __shfl_xor(ss, 2); ss += __shfl_xor(ss, 4); ss += __shfl_xor(ss, 8); ss += __shfl_xor(ss, 16);
;       const float rs = 1.0f / sqrtf(ss * (1.0f / 128.0f) + LN_EPS);
; #pragma unroll
;       for (int d0 = 0; d0 < 4; ++d0) Ow[(long)orow * DM + d0 * 32 + r32_e] = (bf16)f2bf(v[d0] * rs * sw[d0]); }
	v_fma_f32 v18, -v160, v240, v70
	v_fma_f32 v19, -v160, v241, v54
	v_mul_f32_e32 v20, v19, v19
	v_fmac_f32_e32 v20, v18, v18
	s_waitcnt lgkmcnt(0)
	v_add_u32_e32 v244, v12, v8
	v_lshl_add_u32 v244, v244, 7, v138
	v_lshl_add_u32 v244, v244, 2, 0
	ds_read2_b32 v[236:237], v244 offset1:32
	ds_read2_b32 v[238:239], v244 offset0:64 offset1:96
	v_fma_f32 v9, -v160, v242, v44
	v_fmac_f32_e32 v20, v9, v9
	v_fma_f32 v16, -v160, v243, v45
	v_fmac_f32_e32 v20, v16, v16
	s_nop 1
	v_mov_b32_dpp v17, v20 quad_perm:[1,0,3,2] row_mask:0xf bank_mask:0xf
	v_add_f32_e32 v17, v20, v17
	s_nop 1
	v_mov_b32_dpp v20, v17 quad_perm:[2,3,0,1] row_mask:0xf bank_mask:0xf
	v_add_f32_e32 v17, v17, v20
	s_nop 1
	v_mov_b32_dpp v20, v17 row_half_mirror row_mask:0xf bank_mask:0xf
	v_add_f32_e32 v17, v17, v20
	s_nop 1
	v_mov_b32_dpp v20, v17 row_mirror row_mask:0xf bank_mask:0xf
	v_add_f32_e32 v17, v17, v20
	v_mov_b32_e32 v20, v17
	s_nop 1
	v_permlane16_swap_b32_e32 v17, v20
	v_add_f32_e32 v17, v17, v20
	v_fmamk_f32 v17, v17, 0x3c000000, v179
	v_cmp_gt_f32_e32 vcc, s4, v17
	v_mul_f32_e32 v20, 0x4f800000, v17
	s_nop 0
	v_cndmask_b32_e32 v17, v17, v20, vcc
	v_sqrt_f32_e32 v20, v17
	s_nop 0
	v_add_u32_e32 v21, -1, v20
	v_fma_f32 v22, -v21, v20, v17
	v_cmp_ge_f32_e64 s[0:1], 0, v22
	v_add_u32_e32 v22, 1, v20
	s_nop 0
	v_cndmask_b32_e64 v21, v20, v21, s[0:1]
	v_fma_f32 v20, -v22, v20, v17
	v_cmp_lt_f32_e64 s[0:1], 0, v20
	s_nop 1
	v_cndmask_b32_e64 v20, v21, v22, s[0:1]
	v_mul_f32_e32 v21, 0x37800000, v20
	v_cndmask_b32_e32 v20, v20, v21, vcc
	v_cmp_class_f32_e32 vcc, v17, v180
	s_nop 1
	v_cndmask_b32_e32 v17, v20, v17, vcc
	v_div_scale_f32 v20, s[0:1], v17, v17, 1.0
	v_rcp_f32_e32 v21, v20
	s_nop 0
	v_fma_f32 v22, -v20, v21, 1.0
	v_fmac_f32_e32 v21, v22, v21
	v_div_scale_f32 v22, vcc, 1.0, v17, 1.0
	v_mul_f32_e32 v23, v22, v21
	v_fma_f32 v24, -v20, v23, v22
	v_fmac_f32_e32 v23, v24, v21
	v_fma_f32 v20, -v20, v23, v22
	v_div_fmas_f32 v20, v20, v21, v23
	v_div_fixup_f32 v17, v20, v17, 1.0
	v_mul_f32_e32 v18, v18, v17
	v_mul_f32_e32 v18, v34, v18
	v_bfe_u32 v20, v18, 16, 1
	v_add3_u32 v18, v18, v20, s70
	global_store_short_d16_hi v[14:15], v18, off
	v_mul_f32_e32 v18, v19, v17
	v_mul_f32_e32 v18, v35, v18
	v_bfe_u32 v19, v18, 16, 1
	v_mul_f32_e32 v9, v9, v17
	v_add3_u32 v18, v18, v19, s70
	v_mul_f32_e32 v9, v36, v9
	global_store_short_d16_hi v[14:15], v18, off offset:64
	v_bfe_u32 v18, v9, 16, 1
	v_add3_u32 v9, v9, v18, s70
	global_store_short_d16_hi v[14:15], v9, off offset:128
	v_mul_f32_e32 v9, v16, v17
	v_mul_f32_e32 v9, v37, v9
	v_bfe_u32 v16, v9, 16, 1
	v_add3_u32 v9, v9, v16, s70
	global_store_short_d16_hi v[14:15], v9, off offset:192
	v_add_u32_e32 v9, v12, v8
	v_lshl_add_u32 v9, v9, 7, v138
	v_lshl_add_u32 v9, v9, 2, 0
	v_lshlrev_b64 v[12:13], 12, v[12:13]
	v_lshl_add_u64 v[12:13], v[4:5], 0, v[12:13]
	s_waitcnt lgkmcnt(1)
	v_fma_f32 v16, -v160, v236, v69
	v_fma_f32 v17, -v160, v237, v53
	v_mul_f32_e32 v18, v17, v17
	v_fmac_f32_e32 v18, v16, v16
	s_waitcnt lgkmcnt(0)
	v_add_u32_e32 v244, v10, v8
	v_lshl_add_u32 v244, v244, 7, v138
	v_lshl_add_u32 v244, v244, 2, 0
	ds_read2_b32 v[240:241], v244 offset1:32
	ds_read2_b32 v[242:243], v244 offset0:64 offset1:96
	v_fma_f32 v9, -v160, v238, v42
	v_fmac_f32_e32 v18, v9, v9
	v_fma_f32 v14, -v160, v239, v43
	v_fmac_f32_e32 v18, v14, v14
	s_nop 1
	v_mov_b32_dpp v15, v18 quad_perm:[1,0,3,2] row_mask:0xf bank_mask:0xf
	v_add_f32_e32 v15, v18, v15
	s_nop 1
	v_mov_b32_dpp v18, v15 quad_perm:[2,3,0,1] row_mask:0xf bank_mask:0xf
	v_add_f32_e32 v15, v15, v18
	s_nop 1
	v_mov_b32_dpp v18, v15 row_half_mirror row_mask:0xf bank_mask:0xf
	v_add_f32_e32 v15, v15, v18
	s_nop 1
	v_mov_b32_dpp v18, v15 row_mirror row_mask:0xf bank_mask:0xf
	v_add_f32_e32 v15, v15, v18
	v_mov_b32_e32 v18, v15
	s_nop 1
	v_permlane16_swap_b32_e32 v15, v18
	v_add_f32_e32 v15, v15, v18
	v_fmamk_f32 v15, v15, 0x3c000000, v179
	v_cmp_gt_f32_e32 vcc, s4, v15
	v_mul_f32_e32 v18, 0x4f800000, v15
	s_nop 0
	v_cndmask_b32_e32 v15, v15, v18, vcc
	v_sqrt_f32_e32 v18, v15
	s_nop 0
	v_add_u32_e32 v19, -1, v18
	v_fma_f32 v20, -v19, v18, v15
	v_cmp_ge_f32_e64 s[0:1], 0, v20
	v_add_u32_e32 v20, 1, v18
	s_nop 0
	v_cndmask_b32_e64 v19, v18, v19, s[0:1]
	v_fma_f32 v18, -v20, v18, v15
	v_cmp_lt_f32_e64 s[0:1], 0, v18
	s_nop 1
	v_cndmask_b32_e64 v18, v19, v20, s[0:1]
	v_mul_f32_e32 v19, 0x37800000, v18
	v_cndmask_b32_e32 v18, v18, v19, vcc
	v_cmp_class_f32_e32 vcc, v15, v180
	s_nop 1
	v_cndmask_b32_e32 v15, v18, v15, vcc
	v_div_scale_f32 v18, s[0:1], v15, v15, 1.0
	v_rcp_f32_e32 v19, v18
	s_nop 0
	v_fma_f32 v20, -v18, v19, 1.0
	v_fmac_f32_e32 v19, v20, v19
	v_div_scale_f32 v20, vcc, 1.0, v15, 1.0
	v_mul_f32_e32 v21, v20, v19
	v_fma_f32 v22, -v18, v21, v20
	v_fmac_f32_e32 v21, v22, v19
	v_fma_f32 v18, -v18, v21, v20
	v_div_fmas_f32 v18, v18, v19, v21
	v_div_fixup_f32 v15, v18, v15, 1.0
	v_mul_f32_e32 v16, v16, v15
	v_mul_f32_e32 v16, v34, v16
	v_bfe_u32 v18, v16, 16, 1
	v_add3_u32 v16, v16, v18, s70
	global_store_short_d16_hi v[12:13], v16, off
	v_mul_f32_e32 v16, v17, v15
	v_mul_f32_e32 v16, v35, v16
	v_bfe_u32 v17, v16, 16, 1
	v_mul_f32_e32 v9, v9, v15
	v_add3_u32 v16, v16, v17, s70
	v_mul_f32_e32 v9, v36, v9
	global_store_short_d16_hi v[12:13], v16, off offset:64
	v_bfe_u32 v16, v9, 16, 1
	v_add3_u32 v9, v9, v16, s70
	global_store_short_d16_hi v[12:13], v9, off offset:128
	v_mul_f32_e32 v9, v14, v15
	v_mul_f32_e32 v9, v37, v9
	v_bfe_u32 v14, v9, 16, 1
	v_add3_u32 v9, v9, v14, s70
	global_store_short_d16_hi v[12:13], v9, off offset:192
	v_add_u32_e32 v9, v10, v8
	v_lshl_add_u32 v9, v9, 7, v138
	v_lshl_add_u32 v9, v9, 2, 0
	v_lshlrev_b64 v[10:11], 12, v[10:11]
	v_lshl_add_u64 v[10:11], v[4:5], 0, v[10:11]
	s_waitcnt lgkmcnt(1)
; __device__ __forceinline__ unsigned f2bf(float f) { unsigned u = __builtin_bit_cast(unsigned, f); return (u + 0x7fffu + ((u >> 16) & 1u)) >> 16; }
; __device__ __forceinline__ int crow(int r, int hi) { return (r & 3) + 8 * (r >> 2) + 4 * hi; }
; __device__ __forceinline__ void attn_unit(const bf16* __restrict__ Qb, const bf16* __restrict__ Kh, const bf16* __restrict__ Vh, int klat0, int nlt, int kctx0, int NT,
;                                           float lam, float post, const float* __restrict__ subw, bf16* __restrict__ Ob, char* lds) {
;     ...
;     for (int r = 0; r < 16; ++r) { const int orow = crow(r, hi_e); float v[4]; float ss = 0.f;
; #pragma unroll
;       for (int d0 = 0; d0 < 4; ++d0) { v[d0] = o[d0][r] - lam * X[(wq_e * 32 + orow) * 128 + d0 * 32 + r32_e]; ss += v[d0] * v[d0]; }
;       ss += __shfl_xor(ss, 1); ss += __shfl_xor(ss, 2); ss += __shfl_xor(ss, 4); ss += __shfl_xor(ss, 8); ss += __shfl_xor(ss, 16);
;       const float rs = 1.0f / sqrtf(ss * (1.0f / 128.0f) + LN_EPS);
; #pragma unroll
;       for (int d0 = 0; d0 < 4; ++d0) Ow[(long)orow * DM + d0 * 32 + r32_e] = (bf16)f2bf(v[d0] * rs * sw[d0]); }
	v_fma_f32 v14, -v160, v240, v68
	v_fma_f32 v15, -v160, v241, v52
	v_mul_f32_e32 v16, v15, v15
	v_fmac_f32_e32 v16, v14, v14
	s_waitcnt lgkmcnt(0)
	v_add_u32_e32 v244, v6, v8
	v_lshl_add_u32 v244, v244, 7, v138
	v_lshl_add_u32 v244, v244, 2, 0
	ds_read2_b32 v[236:237], v244 offset1:32
	ds_read2_b32 v[238:239], v244 offset0:64 offset1:96
	v_fma_f32 v9, -v160, v242, v40
	v_fmac_f32_e32 v16, v9, v9
	v_fma_f32 v12, -v160, v243, v41
	v_fmac_f32_e32 v16, v12, v12
	s_nop 1
	v_mov_b32_dpp v13, v16 quad_perm:[1,0,3,2] row_mask:0xf bank_mask:0xf
	v_add_f32_e32 v13, v16, v13
	s_nop 1
	v_mov_b32_dpp v16, v13 quad_perm:[2,3,0,1] row_mask:0xf bank_mask:0xf
	v_add_f32_e32 v13, v13, v16
	s_nop 1
	v_mov_b32_dpp v16, v13 row_half_mirror row_mask:0xf bank_mask:0xf
	v_add_f32_e32 v13, v13, v16
	s_nop 1
	v_mov_b32_dpp v16, v13 row_mirror row_mask:0xf bank_mask:0xf
	v_add_f32_e32 v13, v13, v16
	v_mov_b32_e32 v16, v13
	s_nop 1
	v_permlane16_swap_b32_e32 v13, v16
	v_add_f32_e32 v13, v13, v16
	v_fmamk_f32 v13, v13, 0x3c000000, v179
	v_cmp_gt_f32_e32 vcc, s4, v13
	v_mul_f32_e32 v16, 0x4f800000, v13
	s_nop 0
	v_cndmask_b32_e32 v13, v13, v16, vcc
	v_sqrt_f32_e32 v16, v13
	s_nop 0
	v_add_u32_e32 v17, -1, v16
	v_fma_f32 v18, -v17, v16, v13
	v_cmp_ge_f32_e64 s[0:1], 0, v18
	v_add_u32_e32 v18, 1, v16
	s_nop 0
	v_cndmask_b32_e64 v17, v16, v17, s[0:1]
	v_fma_f32 v16, -v18, v16, v13
	v_cmp_lt_f32_e64 s[0:1], 0, v16
	s_nop 1
	v_cndmask_b32_e64 v16, v17, v18, s[0:1]
	v_mul_f32_e32 v17, 0x37800000, v16
	v_cndmask_b32_e32 v16, v16, v17, vcc
	v_cmp_class_f32_e32 vcc, v13, v180
	s_nop 1
	v_cndmask_b32_e32 v13, v16, v13, vcc
	v_div_scale_f32 v16, s[0:1], v13, v13, 1.0
	v_rcp_f32_e32 v17, v16
	s_nop 0
	v_fma_f32 v18, -v16, v17, 1.0
	v_fmac_f32_e32 v17, v18, v17
	v_div_scale_f32 v18, vcc, 1.0, v13, 1.0
	v_mul_f32_e32 v19, v18, v17
	v_fma_f32 v20, -v16, v19, v18
	v_fmac_f32_e32 v19, v20, v17
	v_fma_f32 v16, -v16, v19, v18
	v_div_fmas_f32 v16, v16, v17, v19
	v_div_fixup_f32 v13, v16, v13, 1.0
	v_mul_f32_e32 v14, v14, v13
	v_mul_f32_e32 v14, v34, v14
	v_bfe_u32 v16, v14, 16, 1
	v_add3_u32 v14, v14, v16, s70
	global_store_short_d16_hi v[10:11], v14, off
	v_mul_f32_e32 v14, v15, v13
	v_mul_f32_e32 v14, v35, v14
	v_bfe_u32 v15, v14, 16, 1
	v_mul_f32_e32 v9, v9, v13
	v_add3_u32 v14, v14, v15, s70
	v_mul_f32_e32 v9, v36, v9
	global_store_short_d16_hi v[10:11], v14, off offset:64
	v_bfe_u32 v14, v9, 16, 1
	v_add3_u32 v9, v9, v14, s70
	global_store_short_d16_hi v[10:11], v9, off offset:128
	v_mul_f32_e32 v9, v12, v13
	v_mul_f32_e32 v9, v37, v9
	v_bfe_u32 v12, v9, 16, 1
	v_add3_u32 v9, v9, v12, s70
	global_store_short_d16_hi v[10:11], v9, off offset:192
	v_add_u32_e32 v9, v6, v8
	v_lshl_add_u32 v9, v9, 7, v138
	v_lshl_add_u32 v9, v9, 2, 0
	v_lshlrev_b64 v[6:7], 12, v[6:7]
	v_lshl_add_u64 v[6:7], v[4:5], 0, v[6:7]
	s_waitcnt lgkmcnt(1)
	v_fma_f32 v12, -v160, v236, v67
	v_fma_f32 v13, -v160, v237, v51
	v_mul_f32_e32 v14, v13, v13
	v_fmac_f32_e32 v14, v12, v12
	s_waitcnt lgkmcnt(0)
; __device__ __forceinline__ unsigned f2bf(float f) { unsigned u = __builtin_bit_cast(unsigned, f); return (u + 0x7fffu + ((u >> 16) & 1u)) >> 16; }
; __device__ __forceinline__ int crow(int r, int hi) { return (r & 3) + 8 * (r >> 2) + 4 * hi; }
; __device__ __forceinline__ void attn_unit(const bf16* __restrict__ Qb, const bf16* __restrict__ Kh, const bf16* __restrict__ Vh, int klat0, int nlt, int kctx0, int NT,
;                                           float lam, float post, const float* __restrict__ subw, bf16* __restrict__ Ob, char* lds) {
;     ...
;     for (int r = 0; r < 16; ++r) { const int orow = crow(r, hi_e); float v[4]; float ss = 0.f;
; #pragma unroll
;       for (int d0 = 0; d0 < 4; ++d0) { v[d0] = o[d0][r] - lam * X[(wq_e * 32 + orow) * 128 + d0 * 32 + r32_e]; ss += v[d0] * v[d0]; }
;       ss += __shfl_xor(ss, 1); ss += __shfl_xor(ss, 2); ss += __shfl_xor(ss, 4); ss += __shfl_xor(ss, 8); ss += __shfl_xor(ss, 16);
;       const float rs = 1.0f / sqrtf(ss * (1.0f / 128.0f) + LN_EPS);
; #pragma unroll
;       for (int d0 = 0; d0 < 4; ++d0) Ow[(long)orow * DM + d0 * 32 + r32_e] = (bf16)f2bf(v[d0] * rs * sw[d0]); }
	v_add_u32_e32 v245, v2, v8
	v_lshl_add_u32 v245, v245, 7, v138
	v_lshl_add_u32 v244, v245, 2, 0
	ds_read2_b32 v[240:241], v244 offset1:32
	ds_read2_b32 v[242:243], v244 offset0:64 offset1:96
	v_fma_f32 v9, -v160, v238, v38
	v_fmac_f32_e32 v14, v9, v9
	v_fma_f32 v10, -v160, v239, v39
	v_fmac_f32_e32 v14, v10, v10
	s_nop 1
	v_mov_b32_dpp v11, v14 quad_perm:[1,0,3,2] row_mask:0xf bank_mask:0xf
	v_add_f32_e32 v11, v14, v11
	s_nop 1
	v_mov_b32_dpp v14, v11 quad_perm:[2,3,0,1] row_mask:0xf bank_mask:0xf
	v_add_f32_e32 v11, v11, v14
	s_nop 1
	v_mov_b32_dpp v14, v11 row_half_mirror row_mask:0xf bank_mask:0xf
	v_add_f32_e32 v11, v11, v14
	s_nop 1
	v_mov_b32_dpp v14, v11 row_mirror row_mask:0xf bank_mask:0xf
	v_add_f32_e32 v11, v11, v14
	v_mov_b32_e32 v14, v11
	s_nop 1
	v_permlane16_swap_b32_e32 v11, v14
	v_add_f32_e32 v11, v11, v14
	v_fmamk_f32 v11, v11, 0x3c000000, v179
	v_cmp_gt_f32_e32 vcc, s4, v11
	v_mul_f32_e32 v14, 0x4f800000, v11
	s_nop 0
	v_cndmask_b32_e32 v11, v11, v14, vcc
	v_sqrt_f32_e32 v14, v11
	s_nop 0
	v_add_u32_e32 v15, -1, v14
	v_fma_f32 v16, -v15, v14, v11
	v_cmp_ge_f32_e64 s[0:1], 0, v16
	v_add_u32_e32 v16, 1, v14
	s_nop 0
	v_cndmask_b32_e64 v15, v14, v15, s[0:1]
	v_fma_f32 v14, -v16, v14, v11
	v_cmp_lt_f32_e64 s[0:1], 0, v14
	s_nop 1
	v_cndmask_b32_e64 v14, v15, v16, s[0:1]
	v_mul_f32_e32 v15, 0x37800000, v14
	v_cndmask_b32_e32 v14, v14, v15, vcc
	v_cmp_class_f32_e32 vcc, v11, v180
	s_nop 1
	v_cndmask_b32_e32 v11, v14, v11, vcc
	v_div_scale_f32 v14, s[0:1], v11, v11, 1.0
	v_rcp_f32_e32 v15, v14
	s_nop 0
	v_fma_f32 v16, -v14, v15, 1.0
	v_fmac_f32_e32 v15, v16, v15
	v_div_scale_f32 v16, vcc, 1.0, v11, 1.0
	v_mul_f32_e32 v17, v16, v15
	v_fma_f32 v18, -v14, v17, v16
	v_fmac_f32_e32 v17, v18, v15
	v_fma_f32 v14, -v14, v17, v16
	v_div_fmas_f32 v14, v14, v15, v17
	v_div_fixup_f32 v11, v14, v11, 1.0
	v_mul_f32_e32 v12, v12, v11
	v_mul_f32_e32 v12, v34, v12
	v_bfe_u32 v14, v12, 16, 1
	v_add3_u32 v12, v12, v14, s70
	global_store_short_d16_hi v[6:7], v12, off
	v_mul_f32_e32 v12, v13, v11
	v_mul_f32_e32 v12, v35, v12
	v_bfe_u32 v13, v12, 16, 1
	v_mul_f32_e32 v9, v9, v11
	v_add3_u32 v12, v12, v13, s70
	v_mul_f32_e32 v9, v36, v9
	global_store_short_d16_hi v[6:7], v12, off offset:64
	v_bfe_u32 v12, v9, 16, 1
	v_add3_u32 v9, v9, v12, s70
	global_store_short_d16_hi v[6:7], v9, off offset:128
	v_mul_f32_e32 v9, v10, v11
	v_mul_f32_e32 v9, v37, v9
	v_bfe_u32 v10, v9, 16, 1
	v_add3_u32 v9, v9, v10, s70
	global_store_short_d16_hi v[6:7], v9, off offset:192
	v_add_u32_e32 v6, v2, v8
	v_lshl_add_u32 v6, v6, 7, v138
	v_lshl_add_u32 v8, v6, 2, 0
	v_lshlrev_b64 v[2:3], 12, v[2:3]
	v_lshl_add_u64 v[2:3], v[4:5], 0, v[2:3]
	s_waitcnt lgkmcnt(1)
	v_fma_f32 v9, -v160, v240, v66
	v_fma_f32 v10, -v160, v241, v50
	v_mul_f32_e32 v11, v10, v10
	v_fmac_f32_e32 v11, v9, v9
	s_waitcnt lgkmcnt(0)
	v_fma_f32 v6, -v160, v242, v32
	v_fmac_f32_e32 v11, v6, v6
	v_fma_f32 v7, -v160, v243, v33
	v_fmac_f32_e32 v11, v7, v7
	s_nop 1
	v_mov_b32_dpp v8, v11 quad_perm:[1,0,3,2] row_mask:0xf bank_mask:0xf
	s_waitcnt lgkmcnt(0)
	v_add_f32_e32 v8, v11, v8
	s_nop 1
	v_mov_b32_dpp v11, v8 quad_perm:[2,3,0,1] row_mask:0xf bank_mask:0xf
	s_waitcnt lgkmcnt(0)
	v_add_f32_e32 v8, v8, v11
	s_nop 1
	v_mov_b32_dpp v11, v8 row_half_mirror row_mask:0xf bank_mask:0xf
	s_waitcnt lgkmcnt(0)
	v_add_f32_e32 v8, v8, v11
	s_nop 1
	v_mov_b32_dpp v11, v8 row_mirror row_mask:0xf bank_mask:0xf
	s_waitcnt lgkmcnt(0)
	v_add_f32_e32 v8, v8, v11
	v_mov_b32_e32 v11, v8
	s_nop 1
	v_permlane16_swap_b32_e32 v8, v11
	s_waitcnt lgkmcnt(0)
	v_add_f32_e32 v8, v8, v11
	v_fmamk_f32 v8, v8, 0x3c000000, v179
	v_cmp_gt_f32_e32 vcc, s4, v8
	v_mul_f32_e32 v11, 0x4f800000, v8
	s_nop 0
	v_cndmask_b32_e32 v8, v8, v11, vcc
	v_sqrt_f32_e32 v11, v8
	s_nop 0
	v_add_u32_e32 v12, -1, v11
	v_fma_f32 v13, -v12, v11, v8
	v_cmp_ge_f32_e64 s[0:1], 0, v13
	v_add_u32_e32 v13, 1, v11
	s_nop 0
	v_cndmask_b32_e64 v12, v11, v12, s[0:1]
	v_fma_f32 v11, -v13, v11, v8
	v_cmp_lt_f32_e64 s[0:1], 0, v11
	s_nop 1
	v_cndmask_b32_e64 v11, v12, v13, s[0:1]
	v_mul_f32_e32 v12, 0x37800000, v11
	v_cndmask_b32_e32 v11, v11, v12, vcc
	v_cmp_class_f32_e32 vcc, v8, v180
	s_nop 1
	v_cndmask_b32_e32 v8, v11, v8, vcc
	v_div_scale_f32 v11, s[0:1], v8, v8, 1.0
	v_rcp_f32_e32 v12, v11
	s_nop 0
	v_fma_f32 v13, -v11, v12, 1.0
	v_fmac_f32_e32 v12, v13, v12
	v_div_scale_f32 v13, vcc, 1.0, v8, 1.0
	v_mul_f32_e32 v14, v13, v12
	v_fma_f32 v15, -v11, v14, v13
	v_fmac_f32_e32 v14, v15, v12
	v_fma_f32 v11, -v11, v14, v13
	v_div_fmas_f32 v11, v11, v12, v14
	v_div_fixup_f32 v8, v11, v8, 1.0
	v_mul_f32_e32 v4, v9, v8
	v_mul_f32_e32 v4, v34, v4
	v_bfe_u32 v5, v4, 16, 1
	v_add3_u32 v4, v4, v5, s70
	global_store_short_d16_hi v[2:3], v4, off
	v_mul_f32_e32 v4, v10, v8
	v_mul_f32_e32 v4, v35, v4
	v_bfe_u32 v5, v4, 16, 1
	v_add3_u32 v4, v4, v5, s70
	global_store_short_d16_hi v[2:3], v4, off offset:64
	v_mul_f32_e32 v4, v6, v8
	v_mul_f32_e32 v4, v36, v4
	v_bfe_u32 v5, v4, 16, 1
	v_add3_u32 v4, v4, v5, s70
	global_store_short_d16_hi v[2:3], v4, off offset:128
	v_mul_f32_e32 v4, v7, v8
	v_mul_f32_e32 v4, v37, v4
	v_bfe_u32 v5, v4, 16, 1
	v_add3_u32 v4, v4, v5, s70
	global_store_short_d16_hi v[2:3], v4, off offset:192
	s_branch .LBB0_714
